# grid barrier: members poll the top generation word, unused per-XCD generation bump removed; residual epilogue hand-scheduled; plus earlier prologue/norm changes
# baseline (speedup 1.0000x reference)
.LBB0_551:
	s_and_b64 vcc, exec, s[2:3]
	s_cbranch_vccz .LBB0_561
	v_readlane_b32 s10, v255, 30
	v_readlane_b32 s11, v255, 31
	s_and_b64 vcc, exec, s[10:11]
	s_cbranch_vccnz .Lres_orig
	s_lshl_b32 s2, s17, 8
	s_addk_i32 s2, 0xe000
	s_ashr_i32 s2, s2, 11
	s_mulk_i32 s2, 0x2400
	s_addk_i32 s2, 0x2400
	s_cmp_lt_i32 s17, 32
	s_cselect_b32 s2, 0, s2
	s_lshl_b32 s2, s2, 2
	s_add_u32 s8, s36, s2
	s_addc_u32 s9, s37, 0
	v_readlane_b32 s12, v255, 5
	v_readlane_b32 s13, v255, 6
	s_mov_b64 s[10:11], s[12:13]
	v_readlane_b32 s2, v255, 61
	v_readlane_b32 s3, v255, 62
	s_and_b64 vcc, exec, s[2:3]
	s_cbranch_vccnz .Lres_src
	v_readlane_b32 s10, v255, 53
	v_readlane_b32 s11, v255, 54
	s_cmp_lt_i32 s17, 32
	s_cbranch_scc1 .Lres_src
	v_readlane_b32 s10, v255, 57
	v_readlane_b32 s11, v255, 58
.Lres_src:
	s_lshl_b32 s2, s48, 8
	s_or_b32 s2, s2, s68
	v_lshl_add_u32 v250, v239, 2, s2
	v_lshlrev_b32_e32 v250, 2, v250
	v_lshlrev_b32_e32 v249, 12, v186
	v_add_u32_e32 v248, v249, v250
	s_nop 2
	global_load_dwordx4 v[216:219], v250, s[8:9] offset:0
	global_load_dwordx4 v[220:223], v250, s[8:9] offset:64
	global_load_dwordx4 v[240:243], v250, s[8:9] offset:512
	global_load_dwordx4 v[244:247], v250, s[8:9] offset:576
	global_load_dwordx4 v[130:133], v248, s[10:11] offset:0
	s_add_u32 s14, s10, 0x10000
	s_addc_u32 s15, s11, 0
	global_load_dwordx4 v[134:137], v248, s[14:15] offset:0
	s_add_u32 s14, s10, 0x20000
	s_addc_u32 s15, s11, 0
	global_load_dwordx4 v[138:141], v248, s[14:15] offset:0
	s_add_u32 s14, s10, 0x30000
	s_addc_u32 s15, s11, 0
	global_load_dwordx4 v[142:145], v248, s[14:15] offset:0
	s_add_u32 s14, s10, 0x80000
	s_addc_u32 s15, s11, 0
	global_load_dwordx4 v[146:149], v248, s[14:15] offset:0
	s_add_u32 s14, s10, 0x90000
	s_addc_u32 s15, s11, 0
	global_load_dwordx4 v[150:153], v248, s[14:15] offset:0
	s_add_u32 s14, s10, 0xa0000
	s_addc_u32 s15, s11, 0
	global_load_dwordx4 v[154:157], v248, s[14:15] offset:0
	s_add_u32 s14, s10, 0xb0000
	s_addc_u32 s15, s11, 0
	global_load_dwordx4 v[158:161], v248, s[14:15] offset:0
	global_load_dwordx4 v[162:165], v248, s[10:11] offset:64
	s_add_u32 s14, s10, 0x10000
	s_addc_u32 s15, s11, 0
	global_load_dwordx4 v[188:191], v248, s[14:15] offset:64
	s_add_u32 s14, s10, 0x20000
	s_addc_u32 s15, s11, 0
	global_load_dwordx4 v[192:195], v248, s[14:15] offset:64
	s_add_u32 s14, s10, 0x30000
	s_addc_u32 s15, s11, 0
	global_load_dwordx4 v[196:199], v248, s[14:15] offset:64
	s_add_u32 s14, s10, 0x80000
	s_addc_u32 s15, s11, 0
	global_load_dwordx4 v[200:203], v248, s[14:15] offset:64
	s_add_u32 s14, s10, 0x90000
	s_addc_u32 s15, s11, 0
	global_load_dwordx4 v[204:207], v248, s[14:15] offset:64
	s_add_u32 s14, s10, 0xa0000
	s_addc_u32 s15, s11, 0
	global_load_dwordx4 v[208:211], v248, s[14:15] offset:64
	s_add_u32 s14, s10, 0xb0000
	s_addc_u32 s15, s11, 0
	global_load_dwordx4 v[212:215], v248, s[14:15] offset:64
	s_waitcnt vmcnt(12)
	v_pk_mul_f32 v[216:217], s[28:29], v[216:217]
	v_pk_mul_f32 v[218:219], s[28:29], v[218:219]
	v_pk_mul_f32 v[220:221], s[28:29], v[220:221]
	v_pk_mul_f32 v[222:223], s[28:29], v[222:223]
	v_pk_mul_f32 v[240:241], s[28:29], v[240:241]
	v_pk_mul_f32 v[242:243], s[28:29], v[242:243]
	v_pk_mul_f32 v[244:245], s[28:29], v[244:245]
	v_pk_mul_f32 v[246:247], s[28:29], v[246:247]
	v_pk_fma_f32 v[130:131], v[216:217], v[126:127], v[130:131]
	v_pk_fma_f32 v[132:133], v[218:219], v[128:129], v[132:133]
	v_pk_fma_f32 v[134:135], v[216:217], v[110:111], v[134:135]
	v_pk_fma_f32 v[136:137], v[218:219], v[112:113], v[136:137]
	v_pk_fma_f32 v[138:139], v[216:217], v[94:95], v[138:139]
	v_pk_fma_f32 v[140:141], v[218:219], v[96:97], v[140:141]
	v_pk_fma_f32 v[142:143], v[216:217], v[78:79], v[142:143]
	v_pk_fma_f32 v[144:145], v[218:219], v[80:81], v[144:145]
	global_store_dwordx4 v248, v[130:133], s[12:13] offset:0
	s_add_u32 s2, s12, 0x10000
	s_addc_u32 s3, s13, 0
	global_store_dwordx4 v248, v[134:137], s[2:3] offset:0
	s_add_u32 s2, s12, 0x20000
	s_addc_u32 s3, s13, 0
	global_store_dwordx4 v248, v[138:141], s[2:3] offset:0
	s_add_u32 s2, s12, 0x30000
	s_addc_u32 s3, s13, 0
	global_store_dwordx4 v248, v[142:145], s[2:3] offset:0
	global_load_dwordx4 v[130:133], v248, s[10:11] offset:512
	s_add_u32 s14, s10, 0x10000
	s_addc_u32 s15, s11, 0
	global_load_dwordx4 v[134:137], v248, s[14:15] offset:512
	s_add_u32 s14, s10, 0x20000
	s_addc_u32 s15, s11, 0
	global_load_dwordx4 v[138:141], v248, s[14:15] offset:512
	s_add_u32 s14, s10, 0x30000
	s_addc_u32 s15, s11, 0
	global_load_dwordx4 v[142:145], v248, s[14:15] offset:512
	s_waitcnt vmcnt(16)
	v_pk_fma_f32 v[146:147], v[216:217], v[62:63], v[146:147]
	v_pk_fma_f32 v[148:149], v[218:219], v[64:65], v[148:149]
	v_pk_fma_f32 v[150:151], v[216:217], v[46:47], v[150:151]
	v_pk_fma_f32 v[152:153], v[218:219], v[48:49], v[152:153]
	v_pk_fma_f32 v[154:155], v[216:217], v[30:31], v[154:155]
	v_pk_fma_f32 v[156:157], v[218:219], v[32:33], v[156:157]
	v_pk_fma_f32 v[158:159], v[216:217], v[14:15], v[158:159]
	v_pk_fma_f32 v[160:161], v[218:219], v[16:17], v[160:161]
	s_add_u32 s2, s12, 0x80000
	s_addc_u32 s3, s13, 0
	global_store_dwordx4 v248, v[146:149], s[2:3] offset:0
	s_add_u32 s2, s12, 0x90000
	s_addc_u32 s3, s13, 0
	global_store_dwordx4 v248, v[150:153], s[2:3] offset:0
	s_add_u32 s2, s12, 0xa0000
	s_addc_u32 s3, s13, 0
	global_store_dwordx4 v248, v[154:157], s[2:3] offset:0
	s_add_u32 s2, s12, 0xb0000
	s_addc_u32 s3, s13, 0
	global_store_dwordx4 v248, v[158:161], s[2:3] offset:0
	s_add_u32 s14, s10, 0x80000
	s_addc_u32 s15, s11, 0
	global_load_dwordx4 v[146:149], v248, s[14:15] offset:512
	s_add_u32 s14, s10, 0x90000
	s_addc_u32 s15, s11, 0
	global_load_dwordx4 v[150:153], v248, s[14:15] offset:512
	s_add_u32 s14, s10, 0xa0000
	s_addc_u32 s15, s11, 0
	global_load_dwordx4 v[154:157], v248, s[14:15] offset:512
	s_add_u32 s14, s10, 0xb0000
	s_addc_u32 s15, s11, 0
	global_load_dwordx4 v[158:161], v248, s[14:15] offset:512
	s_waitcnt vmcnt(20)
	v_pk_fma_f32 v[162:163], v[220:221], v[122:123], v[162:163]
	v_pk_fma_f32 v[164:165], v[222:223], v[124:125], v[164:165]
	v_pk_fma_f32 v[188:189], v[220:221], v[106:107], v[188:189]
	v_pk_fma_f32 v[190:191], v[222:223], v[108:109], v[190:191]
	v_pk_fma_f32 v[192:193], v[220:221], v[90:91], v[192:193]
	v_pk_fma_f32 v[194:195], v[222:223], v[92:93], v[194:195]
	v_pk_fma_f32 v[196:197], v[220:221], v[74:75], v[196:197]
	v_pk_fma_f32 v[198:199], v[222:223], v[76:77], v[198:199]
	global_store_dwordx4 v248, v[162:165], s[12:13] offset:64
	s_add_u32 s2, s12, 0x10000
	s_addc_u32 s3, s13, 0
	global_store_dwordx4 v248, v[188:191], s[2:3] offset:64
	s_add_u32 s2, s12, 0x20000
	s_addc_u32 s3, s13, 0
	global_store_dwordx4 v248, v[192:195], s[2:3] offset:64
	s_add_u32 s2, s12, 0x30000
	s_addc_u32 s3, s13, 0
	global_store_dwordx4 v248, v[196:199], s[2:3] offset:64
	global_load_dwordx4 v[162:165], v248, s[10:11] offset:576
	s_add_u32 s14, s10, 0x10000
	s_addc_u32 s15, s11, 0
	global_load_dwordx4 v[188:191], v248, s[14:15] offset:576
	s_add_u32 s14, s10, 0x20000
	s_addc_u32 s15, s11, 0
	global_load_dwordx4 v[192:195], v248, s[14:15] offset:576
	s_add_u32 s14, s10, 0x30000
	s_addc_u32 s15, s11, 0
	global_load_dwordx4 v[196:199], v248, s[14:15] offset:576
	s_waitcnt vmcnt(24)
	v_pk_fma_f32 v[200:201], v[220:221], v[58:59], v[200:201]
	v_pk_fma_f32 v[202:203], v[222:223], v[60:61], v[202:203]
	v_pk_fma_f32 v[204:205], v[220:221], v[42:43], v[204:205]
	v_pk_fma_f32 v[206:207], v[222:223], v[44:45], v[206:207]
	v_pk_fma_f32 v[208:209], v[220:221], v[26:27], v[208:209]
	v_pk_fma_f32 v[210:211], v[222:223], v[28:29], v[210:211]
	v_pk_fma_f32 v[212:213], v[220:221], v[10:11], v[212:213]
	v_pk_fma_f32 v[214:215], v[222:223], v[12:13], v[214:215]
	s_add_u32 s2, s12, 0x80000
	s_addc_u32 s3, s13, 0
	global_store_dwordx4 v248, v[200:203], s[2:3] offset:64
	s_add_u32 s2, s12, 0x90000
	s_addc_u32 s3, s13, 0
	global_store_dwordx4 v248, v[204:207], s[2:3] offset:64
	s_add_u32 s2, s12, 0xa0000
	s_addc_u32 s3, s13, 0
	global_store_dwordx4 v248, v[208:211], s[2:3] offset:64
	s_add_u32 s2, s12, 0xb0000
	s_addc_u32 s3, s13, 0
	global_store_dwordx4 v248, v[212:215], s[2:3] offset:64
	s_add_u32 s14, s10, 0x80000
	s_addc_u32 s15, s11, 0
	global_load_dwordx4 v[200:203], v248, s[14:15] offset:576
	s_add_u32 s14, s10, 0x90000
	s_addc_u32 s15, s11, 0
	global_load_dwordx4 v[204:207], v248, s[14:15] offset:576
	s_add_u32 s14, s10, 0xa0000
	s_addc_u32 s15, s11, 0
	global_load_dwordx4 v[208:211], v248, s[14:15] offset:576
	s_add_u32 s14, s10, 0xb0000
	s_addc_u32 s15, s11, 0
	global_load_dwordx4 v[212:215], v248, s[14:15] offset:576
	s_waitcnt vmcnt(24)
	v_pk_fma_f32 v[130:131], v[240:241], v[118:119], v[130:131]
	v_pk_fma_f32 v[132:133], v[242:243], v[120:121], v[132:133]
	v_pk_fma_f32 v[134:135], v[240:241], v[102:103], v[134:135]
	v_pk_fma_f32 v[136:137], v[242:243], v[104:105], v[136:137]
	v_pk_fma_f32 v[138:139], v[240:241], v[86:87], v[138:139]
	v_pk_fma_f32 v[140:141], v[242:243], v[88:89], v[140:141]
	v_pk_fma_f32 v[142:143], v[240:241], v[70:71], v[142:143]
	v_pk_fma_f32 v[144:145], v[242:243], v[72:73], v[144:145]
	global_store_dwordx4 v248, v[130:133], s[12:13] offset:512
	s_add_u32 s2, s12, 0x10000
	s_addc_u32 s3, s13, 0
	global_store_dwordx4 v248, v[134:137], s[2:3] offset:512
	s_add_u32 s2, s12, 0x20000
	s_addc_u32 s3, s13, 0
	global_store_dwordx4 v248, v[138:141], s[2:3] offset:512
	s_add_u32 s2, s12, 0x30000
	s_addc_u32 s3, s13, 0
	global_store_dwordx4 v248, v[142:145], s[2:3] offset:512
	s_waitcnt vmcnt(20)
	v_pk_fma_f32 v[146:147], v[240:241], v[54:55], v[146:147]
	v_pk_fma_f32 v[148:149], v[242:243], v[56:57], v[148:149]
	v_pk_fma_f32 v[150:151], v[240:241], v[38:39], v[150:151]
	v_pk_fma_f32 v[152:153], v[242:243], v[40:41], v[152:153]
	v_pk_fma_f32 v[154:155], v[240:241], v[22:23], v[154:155]
	v_pk_fma_f32 v[156:157], v[242:243], v[24:25], v[156:157]
	v_pk_fma_f32 v[158:159], v[240:241], v[6:7], v[158:159]
	v_pk_fma_f32 v[160:161], v[242:243], v[8:9], v[160:161]
	s_add_u32 s2, s12, 0x80000
	s_addc_u32 s3, s13, 0
	global_store_dwordx4 v248, v[146:149], s[2:3] offset:512
	s_add_u32 s2, s12, 0x90000
	s_addc_u32 s3, s13, 0
	global_store_dwordx4 v248, v[150:153], s[2:3] offset:512
	s_add_u32 s2, s12, 0xa0000
	s_addc_u32 s3, s13, 0
	global_store_dwordx4 v248, v[154:157], s[2:3] offset:512
	s_add_u32 s2, s12, 0xb0000
	s_addc_u32 s3, s13, 0
	global_store_dwordx4 v248, v[158:161], s[2:3] offset:512
	s_waitcnt vmcnt(16)
	v_pk_fma_f32 v[162:163], v[244:245], v[114:115], v[162:163]
	v_pk_fma_f32 v[164:165], v[246:247], v[116:117], v[164:165]
	v_pk_fma_f32 v[188:189], v[244:245], v[98:99], v[188:189]
	v_pk_fma_f32 v[190:191], v[246:247], v[100:101], v[190:191]
	v_pk_fma_f32 v[192:193], v[244:245], v[82:83], v[192:193]
	v_pk_fma_f32 v[194:195], v[246:247], v[84:85], v[194:195]
	v_pk_fma_f32 v[196:197], v[244:245], v[66:67], v[196:197]
	v_pk_fma_f32 v[198:199], v[246:247], v[68:69], v[198:199]
	global_store_dwordx4 v248, v[162:165], s[12:13] offset:576
	s_add_u32 s2, s12, 0x10000
	s_addc_u32 s3, s13, 0
	global_store_dwordx4 v248, v[188:191], s[2:3] offset:576
	s_add_u32 s2, s12, 0x20000
	s_addc_u32 s3, s13, 0
	global_store_dwordx4 v248, v[192:195], s[2:3] offset:576
	s_add_u32 s2, s12, 0x30000
	s_addc_u32 s3, s13, 0
	global_store_dwordx4 v248, v[196:199], s[2:3] offset:576
	s_waitcnt vmcnt(12)
	v_pk_fma_f32 v[200:201], v[244:245], v[50:51], v[200:201]
	v_pk_fma_f32 v[202:203], v[246:247], v[52:53], v[202:203]
	v_pk_fma_f32 v[204:205], v[244:245], v[34:35], v[204:205]
	v_pk_fma_f32 v[206:207], v[246:247], v[36:37], v[206:207]
	v_pk_fma_f32 v[208:209], v[244:245], v[18:19], v[208:209]
	v_pk_fma_f32 v[210:211], v[246:247], v[20:21], v[210:211]
	v_pk_fma_f32 v[212:213], v[244:245], v[2:3], v[212:213]
	v_pk_fma_f32 v[214:215], v[246:247], v[4:5], v[214:215]
	s_add_u32 s2, s12, 0x80000
	s_addc_u32 s3, s13, 0
	global_store_dwordx4 v248, v[200:203], s[2:3] offset:576
	s_add_u32 s2, s12, 0x90000
	s_addc_u32 s3, s13, 0
	global_store_dwordx4 v248, v[204:207], s[2:3] offset:576
	s_add_u32 s2, s12, 0xa0000
	s_addc_u32 s3, s13, 0
	global_store_dwordx4 v248, v[208:211], s[2:3] offset:576
	s_add_u32 s2, s12, 0xb0000
	s_addc_u32 s3, s13, 0
	global_store_dwordx4 v248, v[212:215], s[2:3] offset:576
	s_branch .LBB0_561
.Lres_orig:
	s_addk_i32 s81, 0xe000
	s_ashr_i32 s2, s81, 11
	s_mulk_i32 s2, 0x2400
	s_add_i32 s10, s2, 0x2400
	s_cmp_lt_i32 s17, 32
	s_cselect_b64 s[2:3], -1, 0
	s_and_b64 s[8:9], s[2:3], exec
	s_cselect_b32 s8, 0, s10
	s_ashr_i32 s9, s8, 31
	s_lshl_b64 s[8:9], s[8:9], 2
	s_add_u32 s8, s36, s8
	s_addc_u32 s9, s37, s9
	s_lshl_b32 s10, s48, 8
	s_or_b32 s10, s10, s68
	v_lshl_add_u32 v200, v239, 2, s10
	v_ashrrev_i32_e32 v201, 31, v200
	v_lshl_add_u64 v[202:203], v[200:201], 2, s[8:9]
	global_load_dwordx4 v[138:141], v[202:203], off
	v_readlane_b32 s10, v255, 30
	v_readlane_b32 s11, v255, 31
	s_andn2_b64 vcc, exec, s[10:11]
	v_mov_b32_e32 v130, 0
	v_cndmask_b32_e64 v0, 0, 1, s[10:11]
	v_readlane_b32 s10, v255, 20
	v_readlane_b32 s11, v255, 21
	v_cmp_ne_u32_e64 s[8:9], 1, v0
	v_mov_b32_e32 v134, 0
	v_lshl_add_u64 v[204:205], v[200:201], 2, s[10:11]
	v_mov_b32_e32 v135, 0
	v_mov_b32_e32 v136, 0
	v_mov_b32_e32 v137, 0
	s_cbranch_vccnz .LBB0_554
	global_load_dwordx4 v[134:137], v[204:205], off

.LBB0_1161:
	s_or_b64 exec, exec, s[8:9]
	v_cvt_f32_u32_e32 v5, v3
	s_waitcnt vmcnt(0)
	v_readfirstlane_b32 s6, v4
	v_sub_u32_e32 v4, 0, v3
	v_rcp_iflag_f32_e32 v5, v5
	v_add_u32_e32 v6, s6, v0
	v_mul_f32_e32 v5, 0x4f7ffffe, v5
	v_cvt_u32_f32_e32 v5, v5
	v_mul_lo_u32 v0, v4, v5
	v_mul_hi_u32 v0, v5, v0
	v_add_u32_e32 v0, v5, v0
	v_mul_hi_u32 v0, v6, v0
	v_mul_lo_u32 v4, v0, v3
	v_sub_u32_e32 v4, v6, v4
	v_add_u32_e32 v5, 1, v0
	v_cmp_ge_u32_e32 vcc, v4, v3
	s_nop 1
	v_cndmask_b32_e32 v0, v0, v5, vcc
	v_sub_u32_e32 v5, v4, v3
	v_cndmask_b32_e32 v4, v4, v5, vcc
	v_add_u32_e32 v5, 1, v0
	v_cmp_ge_u32_e32 vcc, v4, v3
	v_add_u32_e32 v4, 1, v6
	s_nop 0
	v_cndmask_b32_e32 v0, v0, v5, vcc
	v_mul_lo_u32 v5, v3, v0
	v_add_u32_e32 v3, v5, v3
	v_cmp_ne_u32_e32 vcc, v4, v3
	s_and_saveexec_b64 s[6:7], vcc
	s_xor_b64 s[6:7], exec, s[6:7]
	s_cbranch_execz .LBB0_1175
	s_waitcnt lgkmcnt(0)
	v_readlane_b32 s10, v254, 19
	v_readlane_b32 s11, v254, 20
	s_nop 4
	global_load_dword v2, v1, s[10:11] sc1
	s_waitcnt vmcnt(0)
	v_cmp_eq_u32_e32 vcc, v2, v0
	s_and_saveexec_b64 s[8:9], vcc
	s_cbranch_execz .LBB0_1174
	s_mov_b32 s22, 1
	s_mov_b64 s[12:13], 0
	s_branch .LBB0_1165

.LBB0_1193:
	s_bcnt1_i32_b64 s6, s[6:7]
	v_mov_b32_e32 v0, s6
	s_getpc_b64 s[98:99]
